# SSD Y stores widened to 2x dwordx4 via v_permlane32_swap; per-step dt loads only on the scan wave; scan-wave vmcnt waits re-derived
# speedup vs baseline: 1.0166x; 1.0014x over previous
; #define SSD_ISSUE_DT(c_) do { const int c__ = (c_); const float* dp = dtraw + (rowbase + (size_t)c__ * 128 + lane) * 32 + head; dtn0 = dp[0]; dtn1 = dp[64 * 32]; } while (0)
; __device__ __forceinline__ void ssd_item(const Params& p, LAS unsigned char* lds, int bl, int head, int dry) {
;     ...
;     f32x4 cw0, cw1, cw2, cw3, cbv;
;     cw0 = *(const f32x4*)(p.ssd_conv_w + ch); cw1 = *(const f32x4*)(p.ssd_conv_w + CONV_DIM + ch); cw2 = *(const f32x4*)(p.ssd_conv_w + 2 * CONV_DIM + ch); cw3 = *(const f32x4*)(p.ssd_conv_w + 3 * CONV_DIM + ch);
;     cbv = *(const f32x4*)(p.ssd_conv_b + ch);
;     u32x2 raw[35]; float dtn0 = 0.f, dtn1 = 0.f; u32x2 zr[4];
;     const size_t pstep = cact ? (size_t)PLD : (size_t)0;
;     const int ti_d = w >> 1, pc_d = w & 1;
;     ...
;     SSD_ISSUE_DT(0); SSD_ISSUE_RAW(0);
.LBB0_210:
	s_andn2_saveexec_b64 s[0:1], s[0:1]
	v_lshl_add_u32 v0, s12, 6, v2
	v_add_u32_e32 v6, 0x800, v0
	v_mov_b32_e32 v4, 0
	s_andn2_b64 s[4:5], s[4:5], exec
	s_or_b64 exec, exec, s[0:1]
	v_ashrrev_i32_e32 v1, 31, v0
	v_readlane_b32 s6, v245, 25
	v_readlane_b32 s0, v243, 42
	v_lshlrev_b64 v[0:1], 2, v[0:1]
	v_readlane_b32 s56, v245, 29
	v_readlane_b32 s7, v245, 26
	s_ashr_i32 s0, s0, 5
	v_readlane_b32 s62, v245, 35
	v_readlane_b32 s63, v245, 36
	v_lshl_add_u64 v[10:11], s[6:7], 0, v[0:1]
	v_readlane_b32 s6, v245, 27
	s_ashr_i32 s1, s0, 31
	v_lshl_add_u64 v[8:9], s[62:63], 0, v[0:1]
	v_readlane_b32 s7, v245, 28
	s_lshl_b64 s[54:55], s[0:1], 12
	global_load_dwordx4 v[48:51], v[8:9], off
	global_load_dwordx4 v[52:55], v[10:11], off
	v_lshl_add_u64 v[8:9], s[6:7], 0, v[0:1]
	v_readlane_b32 s6, v245, 45
	s_movk_i32 s1, 0x140
	v_readlane_b32 s7, v245, 46
	v_cmp_gt_i32_e64 s[40:41], s1, v246
	s_mul_hi_i32 s1, s0, 0x6400000
	s_mul_i32 s0, s0, 0x6400000
	v_readlane_b32 s64, v245, 37
	v_readlane_b32 s65, v245, 38
	v_lshl_add_u64 v[10:11], s[6:7], 0, v[0:1]
	v_lshl_add_u32 v163, v3, 5, -3
	v_add_u32_e32 v163, s99, v163
	s_add_u32 s0, s14, s0
	global_load_dwordx4 v[56:59], v[8:9], off
	global_load_dwordx4 v[60:63], v[10:11], off
	v_lshl_add_u64 v[0:1], s[64:65], 0, v[0:1]
	v_cndmask_b32_e64 v168, v226, v6, s[40:41]
	v_cndmask_b32_e64 v10, 0, v163, s[40:41]
	s_addc_u32 s1, s15, s1
	global_load_dwordx4 v[64:67], v[0:1], off
	v_cndmask_b32_e64 v12, 0, v225, s[40:41]
	v_lshl_add_u64 v[68:69], v[168:169], 1, s[0:1]
	v_max_i32_e32 v0, 0, v10
	v_max_i32_e32 v6, -1, v10
	v_or_b32_e32 v8, 2, v10
	v_add_u32_e32 v10, 3, v10
	v_mad_u64_u32 v[0:1], s[0:1], v0, s33, v[68:69]
	v_add_u32_e32 v6, 1, v6
	v_max_i32_e32 v8, 0, v8
	v_mad_i64_i32 v[10:11], s[0:1], v10, s33, v[68:69]
	v_lshlrev_b32_e32 v168, 1, v12
	s_cmp_ge_u32 s98, 4
	s_cselect_b32 s100, 0, -1
	v_mov_b32_e32 v247, 0
	v_and_b32_e32 v246, s100, v168
	v_mad_u64_u32 v[6:7], s[0:1], v6, s33, v[68:69]
	v_mad_u64_u32 v[8:9], s[0:1], v8, s33, v[68:69]
	global_load_dwordx2 v[150:151], v[0:1], off
	global_load_dwordx2 v[152:153], v[6:7], off
	global_load_dwordx2 v[154:155], v[8:9], off
	global_load_dwordx2 v[148:149], v[10:11], off
	v_lshl_add_u64 v[0:1], v[10:11], 0, v[168:169]
	v_lshl_add_u64 v[6:7], v[0:1], 0, v[168:169]
	v_lshl_add_u64 v[8:9], v[6:7], 0, v[168:169]
	global_load_dwordx2 v[146:147], v[0:1], off
	global_load_dwordx2 v[144:145], v[6:7], off
	global_load_dwordx2 v[142:143], v[8:9], off
	v_lshl_add_u64 v[0:1], v[8:9], 0, v[168:169]
	global_load_dwordx2 v[140:141], v[0:1], off
	v_lshl_add_u64 v[0:1], v[0:1], 0, v[168:169]
	global_load_dwordx2 v[138:139], v[0:1], off
	v_lshl_add_u64 v[0:1], v[0:1], 0, v[168:169]
	global_load_dwordx2 v[136:137], v[0:1], off
	v_lshl_add_u64 v[0:1], v[0:1], 0, v[168:169]
	global_load_dwordx2 v[134:135], v[0:1], off
	v_lshl_add_u64 v[0:1], v[0:1], 0, v[168:169]
	global_load_dwordx2 v[132:133], v[0:1], off
	v_lshl_add_u64 v[0:1], v[0:1], 0, v[168:169]
	global_load_dwordx2 v[130:131], v[0:1], off
	v_lshl_add_u64 v[0:1], v[0:1], 0, v[168:169]
	global_load_dwordx2 v[128:129], v[0:1], off
	v_lshl_add_u64 v[0:1], v[0:1], 0, v[168:169]
	global_load_dwordx2 v[126:127], v[0:1], off
	v_lshl_add_u64 v[0:1], v[0:1], 0, v[168:169]
	global_load_dwordx2 v[124:125], v[0:1], off
	v_lshl_add_u64 v[0:1], v[0:1], 0, v[168:169]
	global_load_dwordx2 v[122:123], v[0:1], off
	v_lshl_add_u64 v[0:1], v[0:1], 0, v[168:169]
	global_load_dwordx2 v[120:121], v[0:1], off
	v_lshl_add_u64 v[0:1], v[0:1], 0, v[168:169]
	global_load_dwordx2 v[118:119], v[0:1], off
	v_lshl_add_u64 v[0:1], v[0:1], 0, v[168:169]
	global_load_dwordx2 v[116:117], v[0:1], off
	v_lshl_add_u64 v[0:1], v[0:1], 0, v[168:169]
	global_load_dwordx2 v[114:115], v[0:1], off
	v_lshl_add_u64 v[0:1], v[0:1], 0, v[168:169]
	global_load_dwordx2 v[112:113], v[0:1], off
	v_lshl_add_u64 v[0:1], v[0:1], 0, v[168:169]
	global_load_dwordx2 v[110:111], v[0:1], off
	v_lshl_add_u64 v[0:1], v[0:1], 0, v[168:169]
	global_load_dwordx2 v[108:109], v[0:1], off
	v_lshl_add_u64 v[0:1], v[0:1], 0, v[168:169]
	global_load_dwordx2 v[106:107], v[0:1], off
	v_lshl_add_u64 v[0:1], v[0:1], 0, v[168:169]
	global_load_dwordx2 v[102:103], v[0:1], off
	v_lshl_add_u64 v[0:1], v[0:1], 0, v[168:169]
	global_load_dwordx2 v[100:101], v[0:1], off
	v_lshl_add_u64 v[0:1], v[0:1], 0, v[168:169]
	global_load_dwordx2 v[94:95], v[0:1], off
	v_lshl_add_u64 v[0:1], v[0:1], 0, v[168:169]
	global_load_dwordx2 v[92:93], v[0:1], off
	v_lshl_add_u64 v[0:1], v[0:1], 0, v[168:169]
	global_load_dwordx2 v[88:89], v[0:1], off
	v_lshl_add_u64 v[0:1], v[0:1], 0, v[168:169]
	global_load_dwordx2 v[86:87], v[0:1], off
	v_lshl_add_u64 v[0:1], v[0:1], 0, v[168:169]
	global_load_dwordx2 v[84:85], v[0:1], off
	v_lshl_add_u64 v[0:1], v[0:1], 0, v[168:169]
	global_load_dwordx2 v[82:83], v[0:1], off
	v_lshl_add_u64 v[0:1], v[0:1], 0, v[168:169]
	global_load_dwordx2 v[80:81], v[0:1], off
	v_lshl_add_u64 v[0:1], v[0:1], 0, v[168:169]
	global_load_dwordx2 v[78:79], v[0:1], off
	s_waitcnt vmcnt(0)
	v_mul_f32_e32 v1, 0x3fb8aa3b, v5
	v_exp_f32_e32 v165, v1
	v_ashrrev_i32_e32 v0, 6, v160
	v_and_b32_e32 v164, 63, v160
	v_and_b32_e32 v240, 32, v164
	v_lshrrev_b32_e32 v241, 2, v240
	v_sub_u32_e32 v240, v240, v241
	v_mov_b32_e32 v241, 0
	v_or_b32_e32 v70, s54, v164
	v_mov_b32_e32 v71, s55
	v_cmp_ne_u32_e64 s[42:43], 3, v0
	v_cmp_eq_u32_e32 vcc, 3, v0
	v_readlane_b32 s57, v245, 30
	v_readlane_b32 s58, v245, 31
	v_readlane_b32 s59, v245, 32
	v_readlane_b32 s60, v245, 33
	v_readlane_b32 s61, v245, 34
	v_readlane_b32 s66, v245, 39
	v_readlane_b32 s67, v245, 40
	v_readlane_b32 s68, v245, 41
	v_readlane_b32 s69, v245, 42
	v_readlane_b32 s70, v245, 43
	v_readlane_b32 s71, v245, 44
	s_and_saveexec_b64 s[6:7], vcc
	s_cbranch_execz .LBB0_222
	v_readlane_b32 s0, v243, 40
	v_lshlrev_b64 v[6:7], 7, v[70:71]
	v_readlane_b32 s1, v243, 41
	s_nop 1
	v_lshl_add_u64 v[6:7], s[0:1], 0, v[6:7]
	v_lshl_add_u64 v[6:7], v[6:7], 0, s[2:3]
	v_add_co_u32_e32 v8, vcc, 0x2000, v6
	global_load_dword v1, v[6:7], off
	s_nop 0
	v_addc_co_u32_e32 v9, vcc, 0, v7, vcc
	global_load_dword v5, v[8:9], off
	s_mov_b32 s0, 0x41a00000
	s_waitcnt vmcnt(1)
	v_add_f32_e32 v1, v162, v1
	v_cmp_nlt_f32_e32 vcc, s0, v1
	s_and_saveexec_b64 s[8:9], vcc
	s_cbranch_execz .LBB0_217
	v_mul_f32_e32 v1, 0x3fb8aa3b, v1
	v_exp_f32_e32 v1, v1
	s_mov_b32 s0, 0x38d1b717
	v_cmp_ngt_f32_e32 vcc, s0, v1
	s_and_saveexec_b64 s[10:11], vcc
	s_cbranch_execz .LBB0_216
	v_add_f32_e32 v1, 1.0, v1
	s_mov_b32 s0, 0x800000
	v_cmp_gt_f32_e32 vcc, s0, v1
	s_mov_b32 s0, 0x3f317217
	s_nop 0
	v_cndmask_b32_e64 v6, 0, 32, vcc
	v_ldexp_f32 v1, v1, v6
	v_log_f32_e32 v1, v1
	s_nop 0
	v_mul_f32_e32 v6, 0x3f317217, v1
	v_fma_f32 v6, v1, s0, -v6
	v_fmac_f32_e32 v6, 0x3377d1cf, v1
	s_mov_b32 s0, 0x7f800000
	v_fmac_f32_e32 v6, 0x3f317217, v1
	v_cmp_lt_f32_e64 s[0:1], |v1|, s0
	s_nop 1
	v_cndmask_b32_e64 v1, v1, v6, s[0:1]
	v_cndmask_b32_e32 v6, 0, v227, vcc
	v_sub_f32_e32 v1, v1, v6

; __device__ __forceinline__ unsigned cvt_pk_bf16(float lo, float hi) { unsigned r; asm volatile("v_cvt_pk_bf16_f32 %0, %1, %2" : "=v"(r) : "v"(lo), "v"(hi)); return r; }
; __device__ __forceinline__ float bf2f(unsigned short b) { return __uint_as_float(((unsigned)b) << 16); }
; __device__ __forceinline__ float bflo(unsigned u) { return __uint_as_float(u << 16); }
; __device__ __forceinline__ float bfhi(unsigned u) { return __uint_as_float(u & 0xffff0000u); }
; __device__ __forceinline__ float siluf_(float v) { return v * __builtin_amdgcn_rcpf(1.0f + __expf(-v)); }
; __device__ __forceinline__ void ssd_item(const Params& p, LAS unsigned char* lds, int bl, int head, int dry) {
;     ...
;         { const int i = ti_d, pc = pc_d;
;           f32x16 accd, acco;
; #pragma unroll
;           for (int r = 0; r < 16; ++r) { accd[r] = 0.f; acco[r] = 0.f; }
;           accd = mma32_k(XT + pc * 32 * SLD, BMm + i * 32 * SLD, 2 * (i + 1), accd, lane);
;           acco = mma32_k8(SB + pc * 32 * SLD, CM + i * 32 * SLD, acco, lane);
;           const int l = i * 32 + cl; const float ecs = __expf(fcs[l]), dsc = Dh * __builtin_amdgcn_rcpf(fdt[l]);
;           bf16_t* zp = proj + (r0 + l) * PLD + COL_Z + head * 64 + pc * 32 + rsub;
; #pragma unroll
;           for (int g4 = 0; g4 < 4; ++g4) { float y[4];
; #pragma unroll
;               for (int e = 0; e < 4; ++e) { const int pp = pc * 32 + 8 * g4 + rsub + e; y[e] = accd[g4 * 4 + e] + ecs * acco[g4 * 4 + e] + dsc * bf2f(XT[pp * SLD + l]); }
;               const u32x2 z2 = zr[g4];
;               y[0] *= siluf_(bflo(z2.x)); y[1] *= siluf_(bfhi(z2.x)); y[2] *= siluf_(bflo(z2.y)); y[3] *= siluf_(bfhi(z2.y));
;               u32x2 o; o.x = cvt_pk_bf16(y[0], y[1]); o.y = cvt_pk_bf16(y[2], y[3]);
;               if (!dry) *(u32x2*)(zp + 8 * g4) = o; } }
.Lzw_skip:
	s_waitcnt vmcnt(35)
	ds_read_b128 v[156:159], v174 offset:32
	ds_read_b128 v[36:39], v173
	ds_read_b128 v[194:197], v173 offset:32
	ds_read_b128 v[198:201], v174 offset:64
	ds_read_b128 v[202:205], v173 offset:64
	ds_read_b128 v[206:209], v174 offset:96
	ds_read_b128 v[210:213], v173 offset:96
	s_waitcnt lgkmcnt(5)
	v_mfma_f32_32x32x16_bf16 v[32:47], v[32:35], v[36:39], 0
	s_cmp_lg_u32 s62, 32
	s_mov_b32 s58, s62
	s_waitcnt lgkmcnt(4)
	v_mfma_f32_32x32x16_bf16 v[32:47], v[156:159], v[194:197], v[32:47]
	s_waitcnt lgkmcnt(2)
	v_mfma_f32_32x32x16_bf16 v[32:47], v[198:201], v[202:205], v[32:47]
	s_waitcnt lgkmcnt(0)
	v_mfma_f32_32x32x16_bf16 v[32:47], v[206:209], v[210:213], v[32:47]
	ds_read_b128 v[156:159], v174 offset:128
	ds_read_b128 v[194:197], v173 offset:128
	ds_read_b128 v[198:201], v174 offset:160
	ds_read_b128 v[202:205], v173 offset:160
	ds_read_b128 v[206:209], v174 offset:192
	ds_read_b128 v[210:213], v173 offset:192
	ds_read_b128 v[214:217], v174 offset:224
	ds_read_b128 v[236:239], v173 offset:224
	s_waitcnt lgkmcnt(6)
	v_mfma_f32_32x32x16_bf16 v[32:47], v[156:159], v[194:197], v[32:47]
	v_lshl_add_u32 v156, v76, 2, s63
	ds_read2st64_b32 v[156:157], v156 offset1:2
	v_lshl_add_u64 v[196:197], s[36:37], 0, v[76:77]
	v_mad_u64_u32 v[158:159], s[0:1], v196, s33, v[74:75]
	v_mov_b32_e32 v194, s63
	s_waitcnt lgkmcnt(0)
	v_mul_f32_e32 v156, 0x3fb8aa3b, v156
	v_mfma_f32_32x32x16_bf16 v[32:47], v[198:201], v[202:205], v[32:47]
	v_exp_f32_e32 v195, v156
	v_rcp_f32_e32 v156, v157
	ds_read_u16 v198, v190 offset:544
	v_mul_f32_e32 v157, v161, v156
	v_mov_b32_e32 v156, v159
	v_mfma_f32_32x32x16_bf16 v[32:47], v[206:209], v[210:213], v[32:47]
	v_mad_u64_u32 v[196:197], s[0:1], v197, s33, v[156:157]
	v_mov_b32_e32 v159, v196
	v_and_b32_e32 v196, 0xffff0000, v104
	v_mfma_f32_32x32x16_bf16 v[32:47], v[214:217], v[236:239], v[32:47]
	s_nop 11
	v_fmac_f32_e32 v16, v32, v195
	ds_read_u16 v32, v190
	v_fmac_f32_e32 v18, v34, v195
	v_lshlrev_b32_e32 v34, 16, v104
	v_fmac_f32_e32 v17, v33, v195
	ds_read_u16 v33, v190 offset:272
	v_fmac_f32_e32 v19, v35, v195
	s_waitcnt lgkmcnt(1)
	v_lshlrev_b32_e32 v35, 16, v32
	v_mul_f32_e32 v32, 0xbfb8aa3b, v34
	v_exp_f32_e32 v32, v32
	s_waitcnt lgkmcnt(0)
	v_lshlrev_b32_e32 v197, 16, v33
	ds_read_u16 v33, v190 offset:816
	v_fmac_f32_e32 v20, v36, v195
	v_add_f32_e32 v32, 1.0, v32
	v_rcp_f32_e32 v156, v32
	v_fmac_f32_e32 v21, v37, v195
	s_waitcnt lgkmcnt(0)
	v_lshlrev_b32_e32 v33, 16, v33
	v_fmac_f32_e32 v22, v38, v195
	v_pk_mul_f32 v[34:35], v[156:157], v[34:35]
	v_fmac_f32_e32 v23, v39, v195
	v_add_f32_e32 v16, v16, v35
	v_mul_f32_e32 v199, v34, v16
	v_mul_f32_e32 v16, 0xbfb8aa3b, v196
	v_exp_f32_e32 v16, v16
	v_fmac_f32_e32 v24, v40, v195
	v_fmac_f32_e32 v25, v41, v195
	v_fmac_f32_e32 v26, v42, v195
	v_add_f32_e32 v16, 1.0, v16
	v_rcp_f32_e32 v156, v16
	v_fmac_f32_e32 v27, v43, v195
	v_fmac_f32_e32 v28, v44, v195
	v_fmac_f32_e32 v29, v45, v195
	v_pk_mul_f32 v[34:35], v[156:157], v[196:197]
	v_fmac_f32_e32 v30, v46, v195
	v_add_f32_e32 v16, v17, v35
	v_mul_f32_e32 v34, v34, v16
	v_lshlrev_b32_e32 v16, 16, v105
	v_mul_f32_e32 v32, 0xbfb8aa3b, v16
	v_exp_f32_e32 v32, v32
	v_lshlrev_b32_e32 v17, 16, v198
	v_fmac_f32_e32 v31, v47, v195
	v_add_f32_e32 v32, 1.0, v32
	v_rcp_f32_e32 v156, v32
	v_and_b32_e32 v32, 0xffff0000, v105
	v_pk_mul_f32 v[16:17], v[156:157], v[16:17]
	s_nop 0
	v_add_f32_e32 v17, v18, v17
	v_mul_f32_e32 v18, v16, v17
	v_mul_f32_e32 v16, 0xbfb8aa3b, v32
	v_exp_f32_e32 v16, v16
	s_nop 0
	v_add_f32_e32 v16, 1.0, v16
	v_rcp_f32_e32 v156, v16
	s_nop 0
	v_pk_mul_f32 v[16:17], v[156:157], v[32:33]
	s_nop 0
	v_add_f32_e32 v17, v19, v17
	v_mul_f32_e32 v17, v16, v17
	v_cvt_pk_bf16_f32 v200, v199, v34
	v_cvt_pk_bf16_f32 v201, v18, v17
	ds_read_u16 v16, v190 offset:2176
	ds_read_u16 v17, v190 offset:2448
	ds_read_u16 v18, v190 offset:2720
	ds_read_u16 v19, v190 offset:2992
	v_lshlrev_b32_e32 v32, 16, v98
	s_waitcnt lgkmcnt(3)
	v_lshlrev_b32_e32 v33, 16, v16
	v_mul_f32_e32 v16, 0xbfb8aa3b, v32
	v_exp_f32_e32 v16, v16
	s_waitcnt lgkmcnt(2)
	v_lshlrev_b32_e32 v17, 16, v17
	s_waitcnt lgkmcnt(0)
	v_lshlrev_b32_e32 v19, 16, v19
	v_add_f32_e32 v16, 1.0, v16
	v_rcp_f32_e32 v156, v16
	s_nop 0
	v_pk_mul_f32 v[32:33], v[156:157], v[32:33]
	s_nop 0
	v_add_f32_e32 v16, v20, v33
	v_mul_f32_e32 v20, v32, v16
	v_and_b32_e32 v16, 0xffff0000, v98
	v_mul_f32_e32 v32, 0xbfb8aa3b, v16
	v_exp_f32_e32 v32, v32
	s_nop 0
	v_add_f32_e32 v32, 1.0, v32
	v_rcp_f32_e32 v156, v32
	s_nop 0
	v_pk_mul_f32 v[16:17], v[156:157], v[16:17]
	s_nop 0
	v_add_f32_e32 v17, v21, v17
	v_mul_f32_e32 v21, v16, v17
	v_lshlrev_b32_e32 v16, 16, v99
	v_lshlrev_b32_e32 v17, 16, v18
	v_mul_f32_e32 v18, 0xbfb8aa3b, v16
	v_exp_f32_e32 v18, v18
	s_nop 0
	v_add_f32_e32 v18, 1.0, v18
	v_rcp_f32_e32 v156, v18
	v_and_b32_e32 v18, 0xffff0000, v99
	v_pk_mul_f32 v[16:17], v[156:157], v[16:17]
	s_nop 0
	v_add_f32_e32 v17, v22, v17
	v_mul_f32_e32 v22, v16, v17
	v_mul_f32_e32 v16, 0xbfb8aa3b, v18
	v_exp_f32_e32 v16, v16
	s_nop 0
	v_add_f32_e32 v16, 1.0, v16
	v_rcp_f32_e32 v156, v16
	s_nop 0
	v_pk_mul_f32 v[16:17], v[156:157], v[18:19]
	s_nop 0
	v_add_f32_e32 v17, v23, v17
	v_mul_f32_e32 v17, v16, v17
	v_cvt_pk_bf16_f32 v204, v20, v21
	v_cvt_pk_bf16_f32 v205, v22, v17
	ds_read_u16 v16, v190 offset:4352
	ds_read_u16 v17, v190 offset:4624
	ds_read_u16 v18, v190 offset:4896
	ds_read_u16 v19, v190 offset:5168
	v_lshlrev_b32_e32 v20, 16, v96
	s_waitcnt lgkmcnt(3)
	v_lshlrev_b32_e32 v21, 16, v16
	v_mul_f32_e32 v16, 0xbfb8aa3b, v20
	v_exp_f32_e32 v16, v16
	s_waitcnt lgkmcnt(2)
	v_lshlrev_b32_e32 v17, 16, v17
	s_waitcnt lgkmcnt(0)
; __device__ __forceinline__ unsigned cvt_pk_bf16(float lo, float hi) { unsigned r; asm volatile("v_cvt_pk_bf16_f32 %0, %1, %2" : "=v"(r) : "v"(lo), "v"(hi)); return r; }
; __device__ __forceinline__ float bf2f(unsigned short b) { return __uint_as_float(((unsigned)b) << 16); }
; __device__ __forceinline__ float bflo(unsigned u) { return __uint_as_float(u << 16); }
; __device__ __forceinline__ float bfhi(unsigned u) { return __uint_as_float(u & 0xffff0000u); }
; __device__ __forceinline__ float siluf_(float v) { return v * __builtin_amdgcn_rcpf(1.0f + __expf(-v)); }
; __device__ __forceinline__ void ssd_item(const Params& p, LAS unsigned char* lds, int bl, int head, int dry) {
;     ...
;           const int l = i * 32 + cl; const float ecs = __expf(fcs[l]), dsc = Dh * __builtin_amdgcn_rcpf(fdt[l]);
;           bf16_t* zp = proj + (r0 + l) * PLD + COL_Z + head * 64 + pc * 32 + rsub;
; #pragma unroll
;           for (int g4 = 0; g4 < 4; ++g4) { float y[4];
; #pragma unroll
;               for (int e = 0; e < 4; ++e) { const int pp = pc * 32 + 8 * g4 + rsub + e; y[e] = accd[g4 * 4 + e] + ecs * acco[g4 * 4 + e] + dsc * bf2f(XT[pp * SLD + l]); }
;               const u32x2 z2 = zr[g4];
;               y[0] *= siluf_(bflo(z2.x)); y[1] *= siluf_(bfhi(z2.x)); y[2] *= siluf_(bflo(z2.y)); y[3] *= siluf_(bfhi(z2.y));
;               u32x2 o; o.x = cvt_pk_bf16(y[0], y[1]); o.y = cvt_pk_bf16(y[2], y[3]);
;               if (!dry) *(u32x2*)(zp + 8 * g4) = o; } }
;         { const float cd = __expf(fcs[127]);
; #pragma unroll
;           for (int r = 0; r < 16; ++r) accS[r] *= cd;
;           accS = mma32_k8(XT + pt * 32 * SLD, BT + nt * 32 * SLD, accS, lane); }
	v_lshlrev_b32_e32 v19, 16, v19
	v_add_f32_e32 v16, 1.0, v16
	v_rcp_f32_e32 v156, v16
	s_nop 0
	v_pk_mul_f32 v[20:21], v[156:157], v[20:21]
	s_nop 0
	v_add_f32_e32 v16, v24, v21
	v_mul_f32_e32 v20, v20, v16
	v_and_b32_e32 v16, 0xffff0000, v96
	v_mul_f32_e32 v21, 0xbfb8aa3b, v16
	v_exp_f32_e32 v21, v21
	s_nop 0
	v_add_f32_e32 v21, 1.0, v21
	v_rcp_f32_e32 v156, v21
	s_nop 0
	v_pk_mul_f32 v[16:17], v[156:157], v[16:17]
	s_nop 0
	v_add_f32_e32 v17, v25, v17
	v_mul_f32_e32 v21, v16, v17
	v_lshlrev_b32_e32 v16, 16, v97
	v_lshlrev_b32_e32 v17, 16, v18
	v_mul_f32_e32 v18, 0xbfb8aa3b, v16
	v_exp_f32_e32 v18, v18
	s_nop 0
	v_add_f32_e32 v18, 1.0, v18
	v_rcp_f32_e32 v156, v18
	v_and_b32_e32 v18, 0xffff0000, v97
	v_pk_mul_f32 v[16:17], v[156:157], v[16:17]
	s_nop 0
	v_add_f32_e32 v17, v26, v17
	v_mul_f32_e32 v22, v16, v17
	v_mul_f32_e32 v16, 0xbfb8aa3b, v18
	v_exp_f32_e32 v16, v16
	s_nop 0
	v_add_f32_e32 v16, 1.0, v16
	v_rcp_f32_e32 v156, v16
	s_nop 0
	v_pk_mul_f32 v[16:17], v[156:157], v[18:19]
	s_nop 0
	v_add_f32_e32 v17, v27, v17
	v_mul_f32_e32 v17, v16, v17
	v_cvt_pk_bf16_f32 v202, v20, v21
	v_cvt_pk_bf16_f32 v203, v22, v17
	ds_read_u16 v16, v190 offset:6528
	ds_read_u16 v17, v190 offset:6800
	ds_read_u16 v18, v190 offset:7072
	ds_read_u16 v19, v190 offset:7344
	v_lshlrev_b32_e32 v20, 16, v90
	s_waitcnt lgkmcnt(3)
	v_lshlrev_b32_e32 v21, 16, v16
	v_mul_f32_e32 v16, 0xbfb8aa3b, v20
	v_exp_f32_e32 v16, v16
	s_waitcnt lgkmcnt(2)
	v_lshlrev_b32_e32 v17, 16, v17
	s_waitcnt lgkmcnt(0)
	v_lshlrev_b32_e32 v19, 16, v19
	v_add_f32_e32 v16, 1.0, v16
	v_rcp_f32_e32 v156, v16
	s_nop 0
	v_pk_mul_f32 v[20:21], v[156:157], v[20:21]
	s_nop 0
	v_add_f32_e32 v16, v28, v21
	v_mul_f32_e32 v20, v20, v16
	v_and_b32_e32 v16, 0xffff0000, v90
	v_mul_f32_e32 v21, 0xbfb8aa3b, v16
	v_exp_f32_e32 v21, v21
	s_nop 0
	v_add_f32_e32 v21, 1.0, v21
	v_rcp_f32_e32 v156, v21
	s_nop 0
	v_pk_mul_f32 v[16:17], v[156:157], v[16:17]
	s_nop 0
	v_add_f32_e32 v17, v29, v17
	v_mul_f32_e32 v21, v16, v17
	v_lshlrev_b32_e32 v16, 16, v91
	v_lshlrev_b32_e32 v17, 16, v18
	v_mul_f32_e32 v18, 0xbfb8aa3b, v16
	v_exp_f32_e32 v18, v18
	s_nop 0
	v_add_f32_e32 v18, 1.0, v18
	v_rcp_f32_e32 v156, v18
	v_and_b32_e32 v18, 0xffff0000, v91
	v_pk_mul_f32 v[16:17], v[156:157], v[16:17]
	s_nop 0
	v_add_f32_e32 v17, v30, v17
	v_mul_f32_e32 v22, v16, v17
	v_mul_f32_e32 v16, 0xbfb8aa3b, v18
	v_exp_f32_e32 v16, v16
	s_nop 0
	v_add_f32_e32 v16, 1.0, v16
	v_rcp_f32_e32 v156, v16
	s_nop 0
	v_pk_mul_f32 v[16:17], v[156:157], v[18:19]
	s_nop 0
	v_add_f32_e32 v17, v31, v17
	v_mul_f32_e32 v17, v16, v17
	v_cvt_pk_bf16_f32 v206, v20, v21
	v_cvt_pk_bf16_f32 v207, v22, v17
	s_nop 1
	v_permlane32_swap_b32_e32 v200, v202
	v_permlane32_swap_b32_e32 v201, v203
	v_permlane32_swap_b32_e32 v204, v206
	v_permlane32_swap_b32_e32 v205, v207
	v_lshl_add_u64 v[208:209], v[158:159], 0, v[240:241]
	global_store_dwordx4 v[208:209], v[200:203], off
	global_store_dwordx4 v[208:209], v[204:207], off offset:16
	ds_read_b32 v16, v194 offset:508
	s_waitcnt lgkmcnt(0)
	v_mul_f32_e32 v16, 0x3fb8aa3b, v16
	v_exp_f32_e32 v16, v16
	s_nop 0
	v_pk_mul_f32 v[14:15], v[14:15], v[16:17] op_sel_hi:[1,0]
	v_pk_mul_f32 v[12:13], v[12:13], v[16:17] op_sel_hi:[1,0]
	v_pk_mul_f32 v[10:11], v[10:11], v[16:17] op_sel_hi:[1,0]
	v_pk_mul_f32 v[8:9], v[8:9], v[16:17] op_sel_hi:[1,0]
	v_pk_mul_f32 v[6:7], v[6:7], v[16:17] op_sel_hi:[1,0]
	v_pk_mul_f32 v[4:5], v[4:5], v[16:17] op_sel_hi:[1,0]
	v_pk_mul_f32 v[2:3], v[2:3], v[16:17] op_sel_hi:[1,0]
	v_pk_mul_f32 v[0:1], v[0:1], v[16:17] op_sel_hi:[1,0]
	ds_read_b128 v[16:19], v175
	ds_read_b128 v[20:23], v175 offset:32
	ds_read_b128 v[24:27], v176
	ds_read_b128 v[28:31], v176 offset:32
	ds_read_b128 v[32:35], v175 offset:64
	ds_read_b128 v[36:39], v176 offset:64
	ds_read_b128 v[40:43], v175 offset:96
	ds_read_b128 v[44:47], v176 offset:96
	s_waitcnt lgkmcnt(5)
	v_mfma_f32_32x32x16_bf16 v[0:15], v[16:19], v[24:27], v[0:15]
	s_waitcnt lgkmcnt(4)
	v_mfma_f32_32x32x16_bf16 v[0:15], v[20:23], v[28:31], v[0:15]
	s_waitcnt lgkmcnt(2)
	v_mfma_f32_32x32x16_bf16 v[0:15], v[32:35], v[36:39], v[0:15]
	s_waitcnt lgkmcnt(0)
	v_mfma_f32_32x32x16_bf16 v[0:15], v[40:43], v[44:47], v[0:15]
	ds_read_b128 v[16:19], v175 offset:128
	ds_read_b128 v[20:23], v176 offset:128
	ds_read_b128 v[24:27], v175 offset:160
	ds_read_b128 v[28:31], v176 offset:160
	ds_read_b128 v[32:35], v175 offset:192
	ds_read_b128 v[36:39], v176 offset:192
	ds_read_b128 v[40:43], v175 offset:224
	ds_read_b128 v[44:47], v176 offset:224
	s_waitcnt lgkmcnt(6)
	v_mfma_f32_32x32x16_bf16 v[0:15], v[16:19], v[20:23], v[0:15]
	s_waitcnt lgkmcnt(4)
	v_mfma_f32_32x32x16_bf16 v[0:15], v[24:27], v[28:31], v[0:15]
	s_waitcnt lgkmcnt(2)
	v_mfma_f32_32x32x16_bf16 v[0:15], v[32:35], v[36:39], v[0:15]
	s_waitcnt lgkmcnt(0)
	v_mfma_f32_32x32x16_bf16 v[0:15], v[40:43], v[44:47], v[0:15]
	s_cbranch_scc0 .LBB0_203
; __device__ __forceinline__ unsigned short f2bf(float f) { return (unsigned short)(cvt_pk_bf16(f, 0.f) & 0xffffu); }
; #define SSD_ISSUE_DT(c_) do { const int c__ = (c_); const float* dp = dtraw + (rowbase + (size_t)c__ * 128 + lane) * 32 + head; dtn0 = dp[0]; dtn1 = dp[64 * 32]; } while (0)
; __device__ __forceinline__ void ssd_item(const Params& p, LAS unsigned char* lds, int bl, int head, int dry) {
;     ...
;         __syncthreads();
; #pragma unroll
;         for (int r = 0; r < 16; ++r) { const int row = (r & 3) + 8 * (r >> 2) + rsub; SB[(pt * 32 + row) * SLD + nt * 32 + cl] = f2bf(accS[r]); }
;         { const bf16_t* zp = proj + (r0 + ti_d * 32 + cl) * PLD + COL_Z + head * 64 + pc_d * 32 + rsub;
; #pragma unroll
;           for (int g4 = 0; g4 < 4; ++g4) zr[g4] = *(const u32x2*)(zp + 8 * g4); }
;         SSD_ISSUE_DT(c + 1 < 32 ? c + 1 : 31);
;         __builtin_amdgcn_sched_barrier(0);
;         if (cact) {
.LBB0_224:
	s_waitcnt lgkmcnt(0)
	s_barrier
	v_cvt_pk_bf16_f32 v16, v0, v185
	ds_write_b16 v186, v16
	v_cvt_pk_bf16_f32 v16, v1, v185
	ds_write_b16 v186, v16 offset:272
	v_cvt_pk_bf16_f32 v16, v2, v185
	ds_write_b16 v186, v16 offset:544
	v_cvt_pk_bf16_f32 v16, v3, v185
	ds_write_b16 v186, v16 offset:816
	v_cvt_pk_bf16_f32 v16, v4, v185
	ds_write_b16 v186, v16 offset:2176
	v_cvt_pk_bf16_f32 v16, v5, v185
	ds_write_b16 v186, v16 offset:2448
	v_cvt_pk_bf16_f32 v16, v6, v185
	ds_write_b16 v186, v16 offset:2720
	v_cvt_pk_bf16_f32 v16, v7, v185
	ds_write_b16 v186, v16 offset:2992
	v_cvt_pk_bf16_f32 v16, v8, v185
	ds_write_b16 v186, v16 offset:4352
	v_cvt_pk_bf16_f32 v16, v9, v185
	ds_write_b16 v186, v16 offset:4624
	v_cvt_pk_bf16_f32 v16, v10, v185
	ds_write_b16 v186, v16 offset:4896
	v_cvt_pk_bf16_f32 v16, v11, v185
	ds_write_b16 v186, v16 offset:5168
	v_cvt_pk_bf16_f32 v16, v12, v185
	s_lshl_b32 s0, s58, 7
	ds_write_b16 v186, v16 offset:6528
	v_cvt_pk_bf16_f32 v16, v13, v185
	s_bitcmp1_b32 s58, 0
	ds_write_b16 v186, v16 offset:6800
	v_cvt_pk_bf16_f32 v16, v14, v185
	s_cselect_b32 s1, 0x600, 0
	ds_write_b16 v186, v16 offset:7072
	v_cvt_pk_bf16_f32 v16, v15, v185
	s_or_b32 s36, s54, s0
	s_mov_b32 s37, s55
	ds_write_b16 v186, v16 offset:7344
	v_lshl_add_u64 v[16:17], v[72:73], 0, s[36:37]
	s_add_i32 s63, s1, 0
	v_mad_u64_u32 v[18:19], s[0:1], v16, s33, v[74:75]
	s_add_i32 s62, s58, 1
	s_add_i32 s63, s63, 0x22000
	v_mov_b32_e32 v16, v19
	s_lshl_b32 s2, s62, 7
	v_mad_u64_u32 v[16:17], s[0:1], v17, s33, v[16:17]
	s_cmp_eq_u32 s58, 31
	s_cselect_b64 s[0:1], -1, 0
	s_and_b64 s[56:57], s[0:1], exec
	s_cselect_b32 s2, 0xf80, s2
	v_mov_b32_e32 v19, v16
	v_lshl_add_u64 v[16:17], v[70:71], 0, s[2:3]
	v_lshlrev_b64 v[16:17], 7, v[16:17]
	v_lshl_add_u64 v[16:17], s[52:53], 0, v[16:17]
	global_load_dwordx2 v[104:105], v[18:19], off
	global_load_dwordx2 v[98:99], v[18:19], off offset:16
	global_load_dwordx2 v[96:97], v[18:19], off offset:32
	global_load_dwordx2 v[90:91], v[18:19], off offset:48
	s_cmp_lg_u32 s98, 3
	s_cbranch_scc1 .Ldt_skip
	global_load_dword v157, v[16:17], off
	v_add_co_u32_e32 v16, vcc, 0x2000, v16
	s_nop 1
	v_addc_co_u32_e32 v17, vcc, 0, v17, vcc
	global_load_dword v156, v[16:17], off
.Ldt_skip:
	v_mov_b32_e32 v16, 0
	s_and_saveexec_b64 s[56:57], s[40:41]
	s_cbranch_execz .LBB0_242
	s_cmp_lt_u32 s98, 4
	s_cbranch_scc1 .Lcw_skip
	s_waitcnt vmcnt(6)
